# ret_chunk: QK step reads batched (1 LDS wait per ks instead of 3), mask blocks specialised per direction by a scalar branch
# baseline (speedup 1.0000x reference)
; #define MFMA32(a, b, c) __builtin_amdgcn_mfma_f32_32x32x16_bf16((a), (b), (c), 0, 0, 0)
; DI void phase_ret_chunk(PrmC p, int ri, unsigned char* smem, bool skip_ctx_out) {
;     ...
; #pragma unroll
;             for (int ks = 0; ks < 8; ++ks) {
;                 const bf16x8 qf = *(const bf16x8*)(smem + R_QL + ii * RQ_PITCH + (16 * ks + 8 * hh) * 2);
;                 const bf16x8 a = *(const __attribute__((address_space(3))) bf16x8*)(stl + (32 * dvt + r) * RQ_PITCH + (16 * ks + 8 * hh) * 2);
;                 acc = MFMA32(a, qf, acc);
;                 if (use0) { const bf16x8 k0f = *(const bf16x8*)(smem + R_KL + r * RQ_PITCH + (16 * ks + 8 * hh) * 2); Sx0 = MFMA32(k0f, qf, Sx0); }
;                 if (use1) { const bf16x8 k1f = *(const bf16x8*)(smem + R_KL + (32 + r) * RQ_PITCH + (16 * ks + 8 * hh) * 2); Sx1 = MFMA32(k1f, qf, Sx1); }
;             }
.LBB0_348:
	v_mov_b32_e32 v147, v134
	ds_read_b128 v[4:7], v234
	ds_read_b128 v[8:11], v233
	ds_read_b128 v[12:15], v235 offset:17408
	ds_read_b128 v[128:131], v235 offset:26112
	s_waitcnt lgkmcnt(0)
	v_mfma_f32_32x32x16_bf16 v[64:79], v[4:7], v[8:11], 0
	s_and_b64 vcc, exec, s[12:13]
	s_cbranch_vccz .Lrq_s0_0
	v_mfma_f32_32x32x16_bf16 v[80:95], v[12:15], v[8:11], 0
.Lrq_s0_0:
	s_and_b64 vcc, exec, s[14:15]
	s_cbranch_vccz .Lrq_s1_0
	v_mfma_f32_32x32x16_bf16 v[48:63], v[128:131], v[8:11], 0
.Lrq_s1_0:
	ds_read_b128 v[4:7], v234 offset:32
	ds_read_b128 v[8:11], v233 offset:32
	ds_read_b128 v[12:15], v235 offset:17440
	ds_read_b128 v[128:131], v235 offset:26144
	s_waitcnt lgkmcnt(0)
	v_mfma_f32_32x32x16_bf16 v[64:79], v[4:7], v[8:11], v[64:79]
	s_and_b64 vcc, exec, s[12:13]
	s_cbranch_vccz .Lrq_s0_1
	v_mfma_f32_32x32x16_bf16 v[80:95], v[12:15], v[8:11], v[80:95]
.Lrq_s0_1:
	s_and_b64 vcc, exec, s[14:15]
	s_cbranch_vccz .Lrq_s1_1
	v_mfma_f32_32x32x16_bf16 v[48:63], v[128:131], v[8:11], v[48:63]
.Lrq_s1_1:
	ds_read_b128 v[4:7], v234 offset:64
	ds_read_b128 v[8:11], v233 offset:64
	ds_read_b128 v[12:15], v235 offset:17472
	ds_read_b128 v[128:131], v235 offset:26176
	s_waitcnt lgkmcnt(0)
	v_mfma_f32_32x32x16_bf16 v[64:79], v[4:7], v[8:11], v[64:79]
	s_and_b64 vcc, exec, s[12:13]
	s_cbranch_vccz .Lrq_s0_2
	v_mfma_f32_32x32x16_bf16 v[80:95], v[12:15], v[8:11], v[80:95]

; #define MFMA32(a, b, c) __builtin_amdgcn_mfma_f32_32x32x16_bf16((a), (b), (c), 0, 0, 0)
; DI void phase_ret_chunk(PrmC p, int ri, unsigned char* smem, bool skip_ctx_out) {
;     ...
; #pragma unroll
;             for (int ks = 0; ks < 8; ++ks) {
;                 const bf16x8 qf = *(const bf16x8*)(smem + R_QL + ii * RQ_PITCH + (16 * ks + 8 * hh) * 2);
;                 const bf16x8 a = *(const __attribute__((address_space(3))) bf16x8*)(stl + (32 * dvt + r) * RQ_PITCH + (16 * ks + 8 * hh) * 2);
;                 acc = MFMA32(a, qf, acc);
;                 if (use0) { const bf16x8 k0f = *(const bf16x8*)(smem + R_KL + r * RQ_PITCH + (16 * ks + 8 * hh) * 2); Sx0 = MFMA32(k0f, qf, Sx0); }
;                 if (use1) { const bf16x8 k1f = *(const bf16x8*)(smem + R_KL + (32 + r) * RQ_PITCH + (16 * ks + 8 * hh) * 2); Sx1 = MFMA32(k1f, qf, Sx1); }
.Lrq_s1_2:
	ds_read_b128 v[4:7], v234 offset:96
	ds_read_b128 v[8:11], v233 offset:96
	ds_read_b128 v[12:15], v235 offset:17504
	ds_read_b128 v[128:131], v235 offset:26208
	s_waitcnt lgkmcnt(0)
	v_mfma_f32_32x32x16_bf16 v[64:79], v[4:7], v[8:11], v[64:79]
	s_and_b64 vcc, exec, s[12:13]
	s_cbranch_vccz .Lrq_s0_3
	v_mfma_f32_32x32x16_bf16 v[80:95], v[12:15], v[8:11], v[80:95]

; #define MFMA32(a, b, c) __builtin_amdgcn_mfma_f32_32x32x16_bf16((a), (b), (c), 0, 0, 0)
; DI void phase_ret_chunk(PrmC p, int ri, unsigned char* smem, bool skip_ctx_out) {
;     ...
; #pragma unroll
;             for (int ks = 0; ks < 8; ++ks) {
;                 const bf16x8 qf = *(const bf16x8*)(smem + R_QL + ii * RQ_PITCH + (16 * ks + 8 * hh) * 2);
;                 const bf16x8 a = *(const __attribute__((address_space(3))) bf16x8*)(stl + (32 * dvt + r) * RQ_PITCH + (16 * ks + 8 * hh) * 2);
;                 acc = MFMA32(a, qf, acc);
;                 if (use0) { const bf16x8 k0f = *(const bf16x8*)(smem + R_KL + r * RQ_PITCH + (16 * ks + 8 * hh) * 2); Sx0 = MFMA32(k0f, qf, Sx0); }
;                 if (use1) { const bf16x8 k1f = *(const bf16x8*)(smem + R_KL + (32 + r) * RQ_PITCH + (16 * ks + 8 * hh) * 2); Sx1 = MFMA32(k1f, qf, Sx1); }
.Lrq_s1_3:
	ds_read_b128 v[4:7], v234 offset:128
	ds_read_b128 v[8:11], v233 offset:128
	ds_read_b128 v[12:15], v235 offset:17536
	ds_read_b128 v[128:131], v235 offset:26240
	s_waitcnt lgkmcnt(0)
	v_mfma_f32_32x32x16_bf16 v[64:79], v[4:7], v[8:11], v[64:79]
	s_and_b64 vcc, exec, s[12:13]
	s_cbranch_vccz .Lrq_s0_4
	v_mfma_f32_32x32x16_bf16 v[80:95], v[12:15], v[8:11], v[80:95]

; #define MFMA32(a, b, c) __builtin_amdgcn_mfma_f32_32x32x16_bf16((a), (b), (c), 0, 0, 0)
; DI void phase_ret_chunk(PrmC p, int ri, unsigned char* smem, bool skip_ctx_out) {
;     ...
; #pragma unroll
;             for (int ks = 0; ks < 8; ++ks) {
;                 const bf16x8 qf = *(const bf16x8*)(smem + R_QL + ii * RQ_PITCH + (16 * ks + 8 * hh) * 2);
;                 const bf16x8 a = *(const __attribute__((address_space(3))) bf16x8*)(stl + (32 * dvt + r) * RQ_PITCH + (16 * ks + 8 * hh) * 2);
;                 acc = MFMA32(a, qf, acc);
;                 if (use0) { const bf16x8 k0f = *(const bf16x8*)(smem + R_KL + r * RQ_PITCH + (16 * ks + 8 * hh) * 2); Sx0 = MFMA32(k0f, qf, Sx0); }
;                 if (use1) { const bf16x8 k1f = *(const bf16x8*)(smem + R_KL + (32 + r) * RQ_PITCH + (16 * ks + 8 * hh) * 2); Sx1 = MFMA32(k1f, qf, Sx1); }
.Lrq_s1_4:
	ds_read_b128 v[4:7], v234 offset:160
	ds_read_b128 v[8:11], v233 offset:160
	ds_read_b128 v[12:15], v235 offset:17568
	ds_read_b128 v[128:131], v235 offset:26272
	s_waitcnt lgkmcnt(0)
	v_mfma_f32_32x32x16_bf16 v[64:79], v[4:7], v[8:11], v[64:79]
	s_and_b64 vcc, exec, s[12:13]
	s_cbranch_vccz .Lrq_s0_5
	v_mfma_f32_32x32x16_bf16 v[80:95], v[12:15], v[8:11], v[80:95]

; #define MFMA32(a, b, c) __builtin_amdgcn_mfma_f32_32x32x16_bf16((a), (b), (c), 0, 0, 0)
; DI void phase_ret_chunk(PrmC p, int ri, unsigned char* smem, bool skip_ctx_out) {
;     ...
; #pragma unroll
;             for (int ks = 0; ks < 8; ++ks) {
;                 const bf16x8 qf = *(const bf16x8*)(smem + R_QL + ii * RQ_PITCH + (16 * ks + 8 * hh) * 2);
;                 const bf16x8 a = *(const __attribute__((address_space(3))) bf16x8*)(stl + (32 * dvt + r) * RQ_PITCH + (16 * ks + 8 * hh) * 2);
;                 acc = MFMA32(a, qf, acc);
;                 if (use0) { const bf16x8 k0f = *(const bf16x8*)(smem + R_KL + r * RQ_PITCH + (16 * ks + 8 * hh) * 2); Sx0 = MFMA32(k0f, qf, Sx0); }
;                 if (use1) { const bf16x8 k1f = *(const bf16x8*)(smem + R_KL + (32 + r) * RQ_PITCH + (16 * ks + 8 * hh) * 2); Sx1 = MFMA32(k1f, qf, Sx1); }
.Lrq_s1_5:
	ds_read_b128 v[4:7], v234 offset:192
	ds_read_b128 v[8:11], v233 offset:192
	ds_read_b128 v[12:15], v235 offset:17600
	ds_read_b128 v[128:131], v235 offset:26304
	s_waitcnt lgkmcnt(0)
	v_mfma_f32_32x32x16_bf16 v[64:79], v[4:7], v[8:11], v[64:79]
	s_and_b64 vcc, exec, s[12:13]
	s_cbranch_vccz .Lrq_s0_6
	v_mfma_f32_32x32x16_bf16 v[80:95], v[12:15], v[8:11], v[80:95]

; #define MFMA32(a, b, c) __builtin_amdgcn_mfma_f32_32x32x16_bf16((a), (b), (c), 0, 0, 0)
; DI void phase_ret_chunk(PrmC p, int ri, unsigned char* smem, bool skip_ctx_out) {
;     ...
; #pragma unroll
;             for (int ks = 0; ks < 8; ++ks) {
;                 const bf16x8 qf = *(const bf16x8*)(smem + R_QL + ii * RQ_PITCH + (16 * ks + 8 * hh) * 2);
;                 const bf16x8 a = *(const __attribute__((address_space(3))) bf16x8*)(stl + (32 * dvt + r) * RQ_PITCH + (16 * ks + 8 * hh) * 2);
;                 acc = MFMA32(a, qf, acc);
;                 if (use0) { const bf16x8 k0f = *(const bf16x8*)(smem + R_KL + r * RQ_PITCH + (16 * ks + 8 * hh) * 2); Sx0 = MFMA32(k0f, qf, Sx0); }
;                 if (use1) { const bf16x8 k1f = *(const bf16x8*)(smem + R_KL + (32 + r) * RQ_PITCH + (16 * ks + 8 * hh) * 2); Sx1 = MFMA32(k1f, qf, Sx1); }
.Lrq_s1_6:
	ds_read_b128 v[4:7], v234 offset:224
	ds_read_b128 v[8:11], v233 offset:224
	ds_read_b128 v[12:15], v235 offset:17632
	ds_read_b128 v[128:131], v235 offset:26336
	s_waitcnt lgkmcnt(0)
	v_mfma_f32_32x32x16_bf16 v[64:79], v[4:7], v[8:11], v[64:79]
	s_and_b64 vcc, exec, s[12:13]
	s_cbranch_vccz .Lrq_s0_7
	v_mfma_f32_32x32x16_bf16 v[80:95], v[12:15], v[8:11], v[80:95]

; #define MFMA32(a, b, c) __builtin_amdgcn_mfma_f32_32x32x16_bf16((a), (b), (c), 0, 0, 0)
; DI void phase_ret_chunk(PrmC p, int ri, unsigned char* smem, bool skip_ctx_out) {
;     ...
; #pragma unroll
;             for (int i = 0; i < 16; ++i) acc[i] *= rowscale;
;             if (use0) {
; #pragma unroll
;                 for (int i = 0; i < 16; ++i) { const int j = (i & 3) + 8 * (i >> 2) + 4 * hh; const bool keep = dir ? (j >= iil) : (iil >= j); Sx0[i] = keep ? Sx0[i] * (gi0 * gtab[hh * 16 + i]) : 0.f; }
; #pragma unroll
;                 for (int s = 0; s < 2; ++s) {
;                     const bf16x8 pb = pack_step(Sx0, s);
;                     const unsigned char* va = smem + R_VTL + (32 * dvt + r) * RT_PITCH + (16 * s + 4 * hh) * 2;
;                     const uint2 lo = *(const uint2*)va, hi = *(const uint2*)(va + 16);
;                     acc = MFMA32(__builtin_bit_cast(bf16x8, make_uint4(lo.x, lo.y, hi.x, hi.y)), pb, acc);
;                 }
.Lrq_s1_7:
	s_nop 9
	v_pk_mul_f32 v[78:79], v[176:177], v[78:79]
	v_pk_mul_f32 v[76:77], v[174:175], v[76:77]
	v_pk_mul_f32 v[74:75], v[172:173], v[74:75]
	v_pk_mul_f32 v[72:73], v[170:171], v[72:73]
	v_pk_mul_f32 v[70:71], v[168:169], v[70:71]
	v_pk_mul_f32 v[68:69], v[166:167], v[68:69]
	v_pk_mul_f32 v[66:67], v[164:165], v[66:67]
	v_pk_mul_f32 v[64:65], v[154:155], v[64:65]
	s_and_saveexec_b64 s[18:19], s[12:13]
	s_cbranch_execz .LBB0_414
	v_add_u32_e32 v128, v132, v187
	ds_read_b32 v2, v128 offset:34816
	ds_read_b32 v0, v128 offset:34820
	ds_read_b32 v4, v128 offset:34824
	ds_read_b32 v3, v128 offset:34828
	ds_read_b32 v6, v128 offset:34832
	ds_read_b32 v5, v128 offset:34836
	ds_read_b32 v8, v128 offset:34840
	ds_read_b32 v7, v128 offset:34844
	ds_read_b32 v10, v128 offset:34848
	ds_read_b32 v9, v128 offset:34852
	ds_read_b32 v12, v128 offset:34856
	ds_read_b32 v11, v128 offset:34860
	ds_read_b32 v14, v128 offset:34864
	ds_read_b32 v13, v128 offset:34868
	ds_read_b32 v129, v128 offset:34872
	ds_read_b32 v15, v128 offset:34876
	s_waitcnt lgkmcnt(0)
	s_and_b64 vcc, exec, s[10:11]
	s_cbranch_vccz .Lrc_nd_a
	v_cmp_ge_i32_e32 vcc, v147, v142
	v_mul_f32_e32 v2, v236, v2
	v_mul_f32_e32 v2, v80, v2
	v_cndmask_b32_e32 v2, 0, v2, vcc
	v_cmp_gt_i32_e32 vcc, v147, v142
	v_mul_f32_e32 v0, v236, v0
	v_mul_f32_e32 v0, v81, v0
	v_cndmask_b32_e32 v0, 0, v0, vcc
	v_cmp_ge_i32_e32 vcc, v147, v192
	v_mul_f32_e32 v4, v236, v4
	v_mul_f32_e32 v4, v82, v4
	v_cndmask_b32_e32 v4, 0, v4, vcc
	v_cmp_ge_i32_e32 vcc, v147, v193
	v_mul_f32_e32 v3, v236, v3
	v_mul_f32_e32 v3, v83, v3
	v_cndmask_b32_e32 v3, 0, v3, vcc
	v_cmp_ge_i32_e32 vcc, v147, v197
	v_mul_f32_e32 v6, v236, v6
	v_mul_f32_e32 v6, v84, v6
	v_cndmask_b32_e32 v6, 0, v6, vcc
	v_cmp_ge_i32_e32 vcc, v147, v198
	v_mul_f32_e32 v5, v236, v5
	v_mul_f32_e32 v5, v85, v5
	v_cndmask_b32_e32 v5, 0, v5, vcc
	v_cmp_ge_i32_e32 vcc, v147, v199
	v_mul_f32_e32 v8, v236, v8
	v_mul_f32_e32 v8, v86, v8
	v_cndmask_b32_e32 v8, 0, v8, vcc
	v_cmp_ge_i32_e32 vcc, v147, v200
	v_mul_f32_e32 v7, v236, v7
	v_mul_f32_e32 v7, v87, v7
	v_cndmask_b32_e32 v7, 0, v7, vcc
	v_cmp_ge_i32_e32 vcc, v147, v201
	v_mul_f32_e32 v10, v236, v10
	v_mul_f32_e32 v10, v88, v10
	v_cndmask_b32_e32 v10, 0, v10, vcc
	v_cmp_ge_i32_e32 vcc, v147, v202
	v_mul_f32_e32 v9, v236, v9
	v_mul_f32_e32 v9, v89, v9
	v_cndmask_b32_e32 v9, 0, v9, vcc
	v_cmp_ge_i32_e32 vcc, v147, v203
	v_mul_f32_e32 v12, v236, v12
	v_mul_f32_e32 v12, v90, v12
	v_cndmask_b32_e32 v12, 0, v12, vcc
	v_cmp_ge_i32_e32 vcc, v147, v204
	v_mul_f32_e32 v11, v236, v11
	v_mul_f32_e32 v11, v91, v11
	v_cndmask_b32_e32 v11, 0, v11, vcc
	v_cmp_ge_i32_e32 vcc, v147, v205
	v_mul_f32_e32 v14, v236, v14
	v_mul_f32_e32 v14, v92, v14
	v_cndmask_b32_e32 v14, 0, v14, vcc
	v_cmp_ge_i32_e32 vcc, v147, v206
	v_mul_f32_e32 v13, v236, v13
	v_mul_f32_e32 v13, v93, v13
	v_cndmask_b32_e32 v13, 0, v13, vcc
	v_cmp_ge_i32_e32 vcc, v147, v207
	v_mul_f32_e32 v129, v236, v129
	v_mul_f32_e32 v129, v94, v129
	v_cndmask_b32_e32 v80, 0, v129, vcc
	v_cmp_ge_i32_e32 vcc, v147, v208
	v_mul_f32_e32 v15, v236, v15
	v_mul_f32_e32 v15, v95, v15
	v_cndmask_b32_e32 v15, 0, v15, vcc
	s_branch .Lrc_end_a
.Lrc_nd_a:
	v_cmp_ge_i32_e32 vcc, v142, v147
	v_mul_f32_e32 v2, v236, v2
	v_mul_f32_e32 v2, v80, v2
	v_cndmask_b32_e32 v2, 0, v2, vcc
	v_cmp_ge_i32_e32 vcc, v191, v147
	v_mul_f32_e32 v0, v236, v0
	v_mul_f32_e32 v0, v81, v0
	v_cndmask_b32_e32 v0, 0, v0, vcc
	v_cmp_ge_i32_e32 vcc, v192, v147
	v_mul_f32_e32 v4, v236, v4
	v_mul_f32_e32 v4, v82, v4
	v_cndmask_b32_e32 v4, 0, v4, vcc
	v_cmp_ge_i32_e32 vcc, v193, v147
	v_mul_f32_e32 v3, v236, v3
	v_mul_f32_e32 v3, v83, v3
	v_cndmask_b32_e32 v3, 0, v3, vcc
	v_cmp_ge_i32_e32 vcc, v197, v147
	v_mul_f32_e32 v6, v236, v6
	v_mul_f32_e32 v6, v84, v6
	v_cndmask_b32_e32 v6, 0, v6, vcc
	v_cmp_ge_i32_e32 vcc, v198, v147
	v_mul_f32_e32 v5, v236, v5
	v_mul_f32_e32 v5, v85, v5
	v_cndmask_b32_e32 v5, 0, v5, vcc
	v_cmp_ge_i32_e32 vcc, v199, v147
	v_mul_f32_e32 v8, v236, v8
	v_mul_f32_e32 v8, v86, v8
	v_cndmask_b32_e32 v8, 0, v8, vcc
	v_cmp_ge_i32_e32 vcc, v200, v147
	v_mul_f32_e32 v7, v236, v7
	v_mul_f32_e32 v7, v87, v7
	v_cndmask_b32_e32 v7, 0, v7, vcc
	v_cmp_ge_i32_e32 vcc, v201, v147
	v_mul_f32_e32 v10, v236, v10
	v_mul_f32_e32 v10, v88, v10
	v_cndmask_b32_e32 v10, 0, v10, vcc
	v_cmp_ge_i32_e32 vcc, v202, v147
	v_mul_f32_e32 v9, v236, v9
	v_mul_f32_e32 v9, v89, v9
	v_cndmask_b32_e32 v9, 0, v9, vcc
	v_cmp_ge_i32_e32 vcc, v203, v147
	v_mul_f32_e32 v12, v236, v12
	v_mul_f32_e32 v12, v90, v12
	v_cndmask_b32_e32 v12, 0, v12, vcc
	v_cmp_ge_i32_e32 vcc, v204, v147
	v_mul_f32_e32 v11, v236, v11
	v_mul_f32_e32 v11, v91, v11
	v_cndmask_b32_e32 v11, 0, v11, vcc
	v_cmp_ge_i32_e32 vcc, v205, v147
	v_mul_f32_e32 v14, v236, v14
	v_mul_f32_e32 v14, v92, v14
	v_cndmask_b32_e32 v14, 0, v14, vcc
	v_cmp_ge_i32_e32 vcc, v206, v147
	v_mul_f32_e32 v13, v236, v13
	v_mul_f32_e32 v13, v93, v13
	v_cndmask_b32_e32 v13, 0, v13, vcc
	v_cmp_ge_i32_e32 vcc, v207, v147
	v_mul_f32_e32 v129, v236, v129
	v_mul_f32_e32 v129, v94, v129
	v_cndmask_b32_e32 v80, 0, v129, vcc
	v_cmp_ge_i32_e32 vcc, v208, v147
	v_mul_f32_e32 v15, v236, v15
	v_mul_f32_e32 v15, v95, v15
	v_cndmask_b32_e32 v15, 0, v15, vcc
; #define MFMA32(a, b, c) __builtin_amdgcn_mfma_f32_32x32x16_bf16((a), (b), (c), 0, 0, 0)
; DI void phase_ret_chunk(PrmC p, int ri, unsigned char* smem, bool skip_ctx_out) {
;     ...
;                 for (int s = 0; s < 2; ++s) {
;                     const bf16x8 pb = pack_step(Sx0, s);
;                     const unsigned char* va = smem + R_VTL + (32 * dvt + r) * RT_PITCH + (16 * s + 4 * hh) * 2;
;                     const uint2 lo = *(const uint2*)va, hi = *(const uint2*)(va + 16);
;                     acc = MFMA32(__builtin_bit_cast(bf16x8, make_uint4(lo.x, lo.y, hi.x, hi.y)), pb, acc);
;                 }
;             }
;             if (use1) {
; #pragma unroll
;                 for (int i = 0; i < 16; ++i) { const int j = 32 + (i & 3) + 8 * (i >> 2) + 4 * hh; const bool keep = dir ? (j >= iil) : (iil >= j); Sx1[i] = keep ? Sx1[i] * (gi1 * gtab[hh * 16 + i]) : 0.f; }
.Lrc_end_a:
	v_cvt_pk_bf16_f32 v82, v2, v0
	v_cvt_pk_bf16_f32 v83, v4, v3
	v_cvt_pk_bf16_f32 v84, v6, v5
	v_cvt_pk_bf16_f32 v85, v8, v7
	s_nop 1
	v_add_u32_e32 v0, v188, v189
	v_add_u32_e32 v0, 0xd000, v0
	ds_read2_b64 v[2:5], v0 offset1:2
	s_waitcnt lgkmcnt(0)
	v_mfma_f32_32x32x16_bf16 v[64:79], v[2:5], v[82:85], v[64:79]
	v_cvt_pk_bf16_f32 v2, v10, v9
	v_cvt_pk_bf16_f32 v3, v12, v11
	v_cvt_pk_bf16_f32 v4, v14, v13
	v_cvt_pk_bf16_f32 v5, v80, v15
	s_nop 1
	ds_read2_b64 v[6:9], v0 offset0:4 offset1:6
	s_waitcnt lgkmcnt(0)
	v_mfma_f32_32x32x16_bf16 v[64:79], v[6:9], v[2:5], v[64:79]
.LBB0_414:
	s_or_b64 exec, exec, s[18:19]
	s_and_saveexec_b64 s[18:19], s[14:15]
	s_cbranch_execz .LBB0_335
	v_add_u32_e32 v128, v132, v187
	ds_read_b32 v2, v128 offset:34816
	ds_read_b32 v0, v128 offset:34820
	ds_read_b32 v5, v128 offset:34824
	ds_read_b32 v4, v128 offset:34828
	ds_read_b32 v7, v128 offset:34832
	ds_read_b32 v6, v128 offset:34836
	ds_read_b32 v9, v128 offset:34840
	ds_read_b32 v8, v128 offset:34844
	ds_read_b32 v11, v128 offset:34848
	ds_read_b32 v10, v128 offset:34852
	ds_read_b32 v13, v128 offset:34856
	ds_read_b32 v12, v128 offset:34860
	ds_read_b32 v15, v128 offset:34864
	ds_read_b32 v14, v128 offset:34868
	ds_read_b32 v129, v128 offset:34872
	ds_read_b32 v130, v128 offset:34876
	s_waitcnt lgkmcnt(0)
	s_and_b64 vcc, exec, s[10:11]
	s_cbranch_vccz .Lrc_nd_b
	v_cmp_ge_i32_e32 vcc, v147, v190
	v_mul_f32_e32 v2, v145, v2
	v_mul_f32_e32 v2, v48, v2
	v_cndmask_b32_e32 v2, 0, v2, vcc
	v_cmp_ge_i32_e32 vcc, v147, v209
	v_mul_f32_e32 v0, v145, v0
	v_mul_f32_e32 v0, v49, v0
	v_cndmask_b32_e32 v0, 0, v0, vcc
	v_cmp_ge_i32_e32 vcc, v147, v210
	v_mul_f32_e32 v5, v145, v5
	v_mul_f32_e32 v5, v50, v5
	v_cndmask_b32_e32 v5, 0, v5, vcc
	v_cmp_ge_i32_e32 vcc, v147, v211
	v_mul_f32_e32 v4, v145, v4
	v_mul_f32_e32 v4, v51, v4
	v_cndmask_b32_e32 v4, 0, v4, vcc
	v_cmp_ge_i32_e32 vcc, v147, v212
	v_mul_f32_e32 v7, v145, v7
	v_mul_f32_e32 v7, v52, v7
	v_cndmask_b32_e32 v7, 0, v7, vcc
	v_cmp_ge_i32_e32 vcc, v147, v213
	v_mul_f32_e32 v6, v145, v6
	v_mul_f32_e32 v6, v53, v6
	v_cndmask_b32_e32 v6, 0, v6, vcc
	v_cmp_ge_i32_e32 vcc, v147, v214
	v_mul_f32_e32 v9, v145, v9
	v_mul_f32_e32 v9, v54, v9
	v_cndmask_b32_e32 v9, 0, v9, vcc
	v_cmp_ge_i32_e32 vcc, v147, v215
	v_mul_f32_e32 v8, v145, v8
	v_mul_f32_e32 v8, v55, v8
	v_cndmask_b32_e32 v8, 0, v8, vcc
	v_cmp_ge_i32_e32 vcc, v147, v216
	v_mul_f32_e32 v11, v145, v11
	v_mul_f32_e32 v11, v56, v11
	v_cndmask_b32_e32 v11, 0, v11, vcc
	v_cmp_ge_i32_e32 vcc, v147, v217
	v_mul_f32_e32 v10, v145, v10
	v_mul_f32_e32 v10, v57, v10
	v_cndmask_b32_e32 v10, 0, v10, vcc
	v_cmp_ge_i32_e32 vcc, v147, v218
	v_mul_f32_e32 v13, v145, v13
	v_mul_f32_e32 v13, v58, v13
	v_cndmask_b32_e32 v13, 0, v13, vcc
	v_cmp_ge_i32_e32 vcc, v147, v219
	v_mul_f32_e32 v12, v145, v12
	v_mul_f32_e32 v12, v59, v12
	v_cndmask_b32_e32 v12, 0, v12, vcc
	v_cmp_ge_i32_e32 vcc, v147, v220
	v_mul_f32_e32 v15, v145, v15
	v_mul_f32_e32 v15, v60, v15
	v_cndmask_b32_e32 v15, 0, v15, vcc
	v_cmp_ge_i32_e32 vcc, v147, v221
	v_mul_f32_e32 v14, v145, v14
	v_mul_f32_e32 v14, v61, v14
	v_cndmask_b32_e32 v14, 0, v14, vcc
	v_cmp_ge_i32_e32 vcc, v147, v222
	v_mul_f32_e32 v129, v145, v129
	v_mul_f32_e32 v129, v62, v129
	v_cndmask_b32_e32 v49, 0, v129, vcc
	v_cmp_ge_i32_e32 vcc, v147, v223
	v_mul_f32_e32 v130, v145, v130
	v_mul_f32_e32 v130, v63, v130
	v_cndmask_b32_e32 v48, 0, v130, vcc
	s_branch .Lrc_end_b
.Lrc_nd_b:
	v_cmp_ge_i32_e32 vcc, v190, v147
	v_mul_f32_e32 v2, v145, v2
	v_mul_f32_e32 v2, v48, v2
	v_cndmask_b32_e32 v2, 0, v2, vcc
	v_cmp_ge_i32_e32 vcc, v209, v147
	v_mul_f32_e32 v0, v145, v0
	v_mul_f32_e32 v0, v49, v0
	v_cndmask_b32_e32 v0, 0, v0, vcc
	v_cmp_ge_i32_e32 vcc, v210, v147
	v_mul_f32_e32 v5, v145, v5
	v_mul_f32_e32 v5, v50, v5
	v_cndmask_b32_e32 v5, 0, v5, vcc
	v_cmp_ge_i32_e32 vcc, v211, v147
	v_mul_f32_e32 v4, v145, v4
	v_mul_f32_e32 v4, v51, v4
	v_cndmask_b32_e32 v4, 0, v4, vcc
	v_cmp_ge_i32_e32 vcc, v212, v147
	v_mul_f32_e32 v7, v145, v7
	v_mul_f32_e32 v7, v52, v7
	v_cndmask_b32_e32 v7, 0, v7, vcc
	v_cmp_ge_i32_e32 vcc, v213, v147
	v_mul_f32_e32 v6, v145, v6
	v_mul_f32_e32 v6, v53, v6
	v_cndmask_b32_e32 v6, 0, v6, vcc
	v_cmp_ge_i32_e32 vcc, v214, v147
	v_mul_f32_e32 v9, v145, v9
	v_mul_f32_e32 v9, v54, v9
	v_cndmask_b32_e32 v9, 0, v9, vcc
	v_cmp_ge_i32_e32 vcc, v215, v147
	v_mul_f32_e32 v8, v145, v8
	v_mul_f32_e32 v8, v55, v8
	v_cndmask_b32_e32 v8, 0, v8, vcc
	v_cmp_ge_i32_e32 vcc, v216, v147
	v_mul_f32_e32 v11, v145, v11
	v_mul_f32_e32 v11, v56, v11
	v_cndmask_b32_e32 v11, 0, v11, vcc
	v_cmp_ge_i32_e32 vcc, v217, v147
	v_mul_f32_e32 v10, v145, v10
	v_mul_f32_e32 v10, v57, v10
	v_cndmask_b32_e32 v10, 0, v10, vcc
	v_cmp_ge_i32_e32 vcc, v218, v147
	v_mul_f32_e32 v13, v145, v13
	v_mul_f32_e32 v13, v58, v13
	v_cndmask_b32_e32 v13, 0, v13, vcc
	v_cmp_ge_i32_e32 vcc, v219, v147
	v_mul_f32_e32 v12, v145, v12
	v_mul_f32_e32 v12, v59, v12
	v_cndmask_b32_e32 v12, 0, v12, vcc
	v_cmp_ge_i32_e32 vcc, v220, v147
	v_mul_f32_e32 v15, v145, v15
	v_mul_f32_e32 v15, v60, v15
	v_cndmask_b32_e32 v15, 0, v15, vcc
	v_cmp_ge_i32_e32 vcc, v221, v147
	v_mul_f32_e32 v14, v145, v14
	v_mul_f32_e32 v14, v61, v14
	v_cndmask_b32_e32 v14, 0, v14, vcc
	v_cmp_ge_i32_e32 vcc, v222, v147
	v_mul_f32_e32 v129, v145, v129
	v_mul_f32_e32 v129, v62, v129
	v_cndmask_b32_e32 v49, 0, v129, vcc
	v_cmp_ge_i32_e32 vcc, v223, v147
	v_mul_f32_e32 v130, v145, v130
	v_mul_f32_e32 v130, v63, v130
	v_cndmask_b32_e32 v48, 0, v130, vcc
.Lrc_end_b:
	s_branch .LBB0_334
.LBB0_447:
	s_mov_b64 s[6:7], 0
